# XCD-local remap of WKV2 record pairs and RET units; RET Q-fragment loads waited at first use
# speedup vs baseline: 1.0329x; 1.0050x over previous
; __device__ __forceinline__ void ph_wkv2(const Params& p, int jl, int lane, int wave) {
;     ...
;     const int gw = blockIdx.x * NWAVES + wave, NGW = gridDim.x * NWAVES;
;     for (int job = wave < 2 ? blockIdx.x * 2 + wave : BATCH * WH * 4; job < BATCH * WH * 4; job += gridDim.x * 2) {
; __global__ void __launch_bounds__(NTHR, 2) mega(Params p, int lo, int hi) {
;     ...
;     (void)xcd_barrier_post((unsigned*)(p.ws + WS_CTL), bst, threadIdx.x == 0);
;     for (int ph = lo; ph < hi; ++ph) {
;         int lid_; asm volatile("v_mbcnt_lo_u32_b32 %0, -1, 0\n\tv_mbcnt_hi_u32_b32 %0, -1, %0" : "=v"(lid_));
;         int tid = wave0 * 64 + lid_; asm volatile("" : "+v"(tid));
;         const int lane = tid & 63, wave = __builtin_amdgcn_readfirstlane(tid >> 6);
;         unsigned char* ws = p.ws;
;         const Ph P = phase_at(ph);
;         const int li = P.layer, jl = li >> 1;
;         const bf16* gA = nullptr; const bf16* gB = nullptr; int gN = 0, gK = 0; EpiAnyT<0> E{}; E.jl = jl; E.ws = ws; E.slot = -1; E.amul = 1.f; E.li = li; E.ldsb = lds; bool is_gemm = false;
.LBB0_6:
	s_and_b32 s39, s6, 0xffffffc0
	s_add_u32 s2, s66, 0x201c0000
	s_addc_u32 s3, s67, 0
	v_writelane_b32 v252, s2, 8
	s_load_dwordx16 s[40:55], s[0:1], 0x40
	s_mov_b32 s95, 0
	v_writelane_b32 v252, s3, 9
	s_add_u32 s2, s66, 0x7600000
	v_writelane_b32 v252, s2, 10
	s_addc_u32 s2, s67, 0
	s_add_u32 s90, s66, 0x446b1000
	s_addc_u32 s91, s67, 0
	v_writelane_b32 v252, s2, 11
	s_add_u32 s2, s66, 0x4a00000
	v_writelane_b32 v252, s2, 12
	s_addc_u32 s2, s67, 0
	s_add_u32 s20, s66, 0x42630000
	s_addc_u32 s21, s67, 0
	v_writelane_b32 v252, s2, 13
	s_add_u32 s2, s66, 0x4600000
	v_writelane_b32 v252, s2, 14
	s_addc_u32 s2, s67, 0
	v_writelane_b32 v252, s2, 15
	s_add_u32 s2, s66, 0x41a00000
	s_addc_u32 s3, s67, 0
	s_add_u32 s62, s66, 0x4000000
	v_writelane_b32 v252, s2, 16
	s_addc_u32 s63, s67, 0
	s_mov_b32 s94, s92
	v_writelane_b32 v252, s3, 17
	s_add_u32 s2, s66, 0xcd00800
	s_addc_u32 s3, s67, 0
	s_add_u32 s36, s66, 0x2400000
	s_addc_u32 s37, s67, 0
	s_add_u32 s22, s66, 0x29400000
	v_writelane_b32 v252, s2, 18
	s_addc_u32 s23, s67, 0
	v_mov_b32_e32 v1, 0
	v_writelane_b32 v252, s3, 19
	s_add_u32 s2, s66, 0x1c00000
	v_writelane_b32 v252, s2, 20
	s_addc_u32 s2, s67, 0
	v_writelane_b32 v252, s2, 21
	s_add_u32 s2, s66, 0x400000
	s_addc_u32 s24, s67, 0
	s_add_u32 s88, s0, 0x138
	v_writelane_b32 v252, s2, 22
	s_addc_u32 s89, s1, 0
	s_ashr_i32 s2, s92, 31
	s_add_u32 s4, s66, 0x46770000
	s_addc_u32 s5, s67, 0
	v_writelane_b32 v252, s4, 23
	v_mov_b32_e32 v222, 0x358637bd
	v_mov_b32_e32 v224, 0x3727c5ac
	v_writelane_b32 v252, s5, 24
	v_writelane_b32 v252, s2, 25
	s_lshr_b32 s2, s2, 29
	s_add_i32 s2, s92, s2
	s_ashr_i32 s3, s2, 3
	s_and_b32 s2, s2, -8
	v_writelane_b32 v252, s3, 26
	s_sub_i32 s2, s92, s2
	v_writelane_b32 v252, s2, 27
	s_add_u32 s2, s66, 0x100000
	s_addc_u32 s3, s67, 0
	v_writelane_b32 v252, s2, 28
	s_load_dwordx16 s[4:19], s[0:1], 0x0
	v_mov_b32_e32 v230, v1
	v_writelane_b32 v252, s3, 29
	s_add_u32 s2, s66, 0x14f00000
	s_addc_u32 s3, s67, 0
	v_writelane_b32 v252, s2, 30
	v_mov_b32_e32 v231, v1
	v_mov_b32_e32 v232, v1
	v_writelane_b32 v252, s3, 31
	s_add_u32 s2, s66, 0x31600000
	s_addc_u32 s3, s67, 0
	v_writelane_b32 v252, s2, 32
	v_mov_b32_e32 v233, v1
	v_mov_b32_e32 v227, 0x42800000
	v_writelane_b32 v252, s3, 33
	s_add_u32 s2, s64, 0x2a640000
	v_writelane_b32 v252, s2, 34
	s_addc_u32 s2, s65, 0
	v_writelane_b32 v252, s2, 35
	s_add_u32 s2, s64, 0x6490000
	v_writelane_b32 v252, s2, 36
	s_addc_u32 s2, s65, 0
	s_cmpk_lt_i32 s92, 0x100
	v_writelane_b32 v252, s2, 37
	s_cselect_b64 s[2:3], -1, 0
	v_writelane_b32 v252, s2, 38
	v_not_b32_e32 v228, 63
	v_mov_b32_e32 v225, 0x40000
	v_writelane_b32 v252, s3, 39
	s_add_u32 s2, s66, 0x19000000
	s_addc_u32 s3, s67, 0
	v_writelane_b32 v252, s2, 40
	v_mov_b32_e32 v229, 0x46800000
	v_not_b32_e32 v226, 31
	v_writelane_b32 v252, s3, 41
	s_add_u32 s2, s66, 0x10e00000
	s_addc_u32 s3, s67, 0
	v_writelane_b32 v252, s2, 42
	v_mov_b32_e32 v223, 0x7fc00000
	s_movk_i32 s33, 0x6000
	v_writelane_b32 v252, s3, 43
	s_add_u32 s2, s66, 0x25300000
	s_addc_u32 s3, s67, 0
	v_writelane_b32 v252, s2, 44
	s_add_u32 s30, s66, 0x2d500000
	s_addc_u32 s31, s67, 0
	v_writelane_b32 v252, s3, 45
	s_and_b32 s2, s92, 7
	s_lshl_b32 s2, s2, 6
	s_lshr_b32 s3, s92, 3
	s_lshl_b32 s3, s3, 1
	s_or_b32 s2, s2, s3
	v_writelane_b32 v252, s2, 46
	s_add_u32 s2, s66, 0x46f90100
	v_writelane_b32 v252, s2, 47
	s_addc_u32 s2, s67, 0
	v_writelane_b32 v252, s2, 48
	s_add_u32 s2, s64, 0x6080000
	s_addc_u32 s3, s65, 0
	v_writelane_b32 v252, s2, 49
	s_mov_b32 s29, 0x46f9d000
	s_movk_i32 s26, 0x84
	v_writelane_b32 v252, s3, 50
	s_mul_i32 s2, s92, 6
	s_add_i32 s2, s2, -2
	v_writelane_b32 v252, s2, 51
	s_add_u32 s2, s64, 0x26540000
	v_writelane_b32 v252, s2, 52
	s_addc_u32 s2, s65, 0
	v_writelane_b32 v252, s2, 53
	s_add_u32 s2, s66, 0x21200000
	s_addc_u32 s3, s67, 0
	v_writelane_b32 v252, s2, 54
	s_mov_b64 s[96:97], 0x80
	s_mov_b32 s93, s24
	v_writelane_b32 v252, s3, 55
	s_add_u32 s2, s66, 0x14f00800
	v_writelane_b32 v252, s2, 56
	s_addc_u32 s2, s67, 0
	v_writelane_b32 v252, s2, 57
	s_add_u32 s2, s64, 0x4080000
	v_writelane_b32 v252, s2, 58
	s_addc_u32 s2, s65, 0
	s_cmpk_lt_i32 s92, 0x200
	v_writelane_b32 v252, s2, 59
	s_cselect_b64 s[2:3], -1, 0
	v_writelane_b32 v252, s2, 60
	s_nop 1
	v_writelane_b32 v252, s3, 61
	s_lshl_b32 s2, s92, 6
	v_writelane_b32 v252, s2, 62
	s_add_u32 s2, s66, 0x1d100000
	s_addc_u32 s3, s67, 0
	v_writelane_b32 v252, s2, 63
	s_nop 1
	v_writelane_b32 v253, s3, 0
	s_lshl_b32 s2, s92, 3
	v_writelane_b32 v253, s2, 1
	s_add_u32 s2, s64, 0x4000000
	s_addc_u32 s3, s65, 0
	s_add_u32 s34, s66, 0xcd00000
	v_writelane_b32 v253, s2, 2
	s_addc_u32 s35, s67, 0
	s_nop 0
	v_writelane_b32 v253, s3, 3
	s_add_u32 s2, s64, 0x2a540000
	s_addc_u32 s3, s65, 0
	v_writelane_b32 v253, s2, 4
	s_nop 1
	v_writelane_b32 v253, s3, 5
	s_add_u32 s2, s64, 0x6480000
	s_addc_u32 s3, s65, 0
	v_writelane_b32 v253, s2, 6
	s_nop 1
	v_writelane_b32 v253, s3, 7
	s_add_u32 s2, s66, 0x3200000
	s_addc_u32 s3, s67, 0
	v_writelane_b32 v253, s2, 8
	s_waitcnt lgkmcnt(0)
; __global__ void __launch_bounds__(NTHR, 2) mega(Params p, int lo, int hi) {
;     ...
;         unsigned char* ws = p.ws;
;         const Ph P = phase_at(ph);
;         const int li = P.layer, jl = li >> 1;
;         const bf16* gA = nullptr; const bf16* gB = nullptr; int gN = 0, gK = 0; EpiAnyT<0> E{}; E.jl = jl; E.ws = ws; E.slot = -1; E.amul = 1.f; E.li = li; E.ldsb = lds; bool is_gemm = false;
	s_cmp_eq_u64 s[40:41], 0
	v_writelane_b32 v253, s3, 9
	s_cselect_b64 s[2:3], -1, 0
	v_writelane_b32 v253, s2, 10
	s_cmp_lg_u64 s[40:41], 0
	s_nop 0
	v_writelane_b32 v253, s3, 11
	s_cselect_b64 s[2:3], -1, 0
	v_writelane_b32 v253, s2, 12
	s_nop 1
	v_writelane_b32 v253, s3, 13
	s_add_u32 s2, s50, 0x9000
	s_addc_u32 s3, s51, 0
	v_writelane_b32 v253, s2, 14
	s_cmp_lg_u64 s[50:51], 0
	s_nop 0
	v_writelane_b32 v253, s3, 15
	s_cselect_b64 s[2:3], -1, 0
	v_writelane_b32 v253, s2, 16
	s_cmp_eq_u64 s[18:19], 0
	s_nop 0
	v_writelane_b32 v253, s3, 17
	s_cselect_b64 s[2:3], -1, 0
	v_writelane_b32 v253, s2, 18
	s_nop 1
	v_writelane_b32 v253, s3, 19
	v_writelane_b32 v253, s4, 20
	s_cmp_lg_u64 s[18:19], 0
	s_cselect_b64 s[2:3], -1, 0
	v_writelane_b32 v253, s5, 21
	v_writelane_b32 v253, s6, 22
	v_writelane_b32 v253, s7, 23
	v_writelane_b32 v253, s8, 24
	v_writelane_b32 v253, s9, 25
	v_writelane_b32 v253, s10, 26
	v_writelane_b32 v253, s11, 27
	v_writelane_b32 v253, s12, 28
	v_writelane_b32 v253, s13, 29
	v_writelane_b32 v253, s14, 30
	v_writelane_b32 v253, s15, 31
	v_writelane_b32 v253, s16, 32
	v_writelane_b32 v253, s17, 33
	v_writelane_b32 v253, s18, 34
	v_writelane_b32 v253, s19, 35
	v_writelane_b32 v253, s2, 36
	s_mov_b32 s6, s95
	s_mov_b32 s7, s95
	v_writelane_b32 v253, s3, 37
	s_lshl_b64 s[2:3], s[94:95], 9
	v_writelane_b32 v253, s2, 38
	s_nop 1
	v_writelane_b32 v253, s3, 39
	s_add_u32 s2, s66, 0x200
	s_addc_u32 s3, s67, 0
	v_writelane_b32 v253, s2, 40
	s_nop 1
	v_writelane_b32 v253, s3, 41
	s_add_u32 s2, s66, 0x1000
	s_addc_u32 s3, s67, 0
	v_writelane_b32 v253, s2, 42
	s_nop 1
	v_writelane_b32 v253, s3, 43
	s_add_u32 s2, s66, 0x1100
	s_addc_u32 s3, s67, 0
	v_writelane_b32 v253, s2, 44
	s_nop 1
	v_writelane_b32 v253, s3, 45
	s_add_u32 s2, s66, 0x1200
	s_addc_u32 s3, s67, 0
	v_writelane_b32 v253, s2, 46
	s_nop 1
	v_writelane_b32 v253, s3, 47
	s_add_u32 s2, s66, 0x1300
	s_addc_u32 s3, s67, 0
	v_writelane_b32 v253, s2, 48
	s_nop 1
	v_writelane_b32 v253, s3, 49
	s_add_u32 s2, s66, 0x3400
	s_addc_u32 s3, s67, 0
	v_writelane_b32 v253, s2, 50
	s_nop 1
	v_writelane_b32 v253, s3, 51
	s_add_u32 s2, s66, 0x3500
	s_addc_u32 s3, s67, 0
	v_writelane_b32 v253, s2, 52
	s_lshl_b64 s[4:5], s[94:95], 12
	s_nop 0
	v_writelane_b32 v253, s3, 53
	s_lshl_b32 s2, s92, 12
	v_writelane_b32 v253, s2, 54
	s_add_u32 s2, s66, s4
	v_writelane_b32 v253, s4, 55
	s_addc_u32 s3, s67, s5
	s_add_u32 s2, s2, 0x100000
	v_writelane_b32 v253, s5, 56
	s_addc_u32 s3, s3, 0
	v_writelane_b32 v253, s2, 57
	s_mov_b32 s4, s95
	s_mov_b32 s5, s95
	v_writelane_b32 v253, s3, 58
	v_writelane_b32 v253, s4, 59
	s_add_i32 s2, 0, 0x10800
	s_nop 0
	v_writelane_b32 v253, s5, 60
	v_writelane_b32 v253, s6, 61
	v_writelane_b32 v253, s7, 62
	v_writelane_b32 v253, s2, 63
	s_add_i32 s2, 0, 0x15000
	v_writelane_b32 v254, s2, 0
	s_add_i32 s2, 0, 0x15020
	s_load_dwordx16 s[4:19], s[0:1], 0x80
	v_writelane_b32 v254, s2, 1
	s_add_i32 s2, 0, 0x20000
	v_writelane_b32 v254, s2, 2
	s_add_i32 s2, 0, 0x23ff0
	v_writelane_b32 v254, s2, 3
	s_add_i32 s2, 0, 0x23ff4
	v_writelane_b32 v254, s2, 4
	s_waitcnt lgkmcnt(0)
	v_writelane_b32 v254, s4, 5
	s_nop 1
	v_writelane_b32 v254, s5, 6
	v_writelane_b32 v254, s6, 7
	v_writelane_b32 v254, s7, 8
	v_writelane_b32 v254, s8, 9
	v_writelane_b32 v254, s9, 10
	v_writelane_b32 v254, s10, 11
	v_writelane_b32 v254, s11, 12
	v_writelane_b32 v254, s12, 13
	v_writelane_b32 v254, s13, 14
	v_writelane_b32 v254, s14, 15
	v_writelane_b32 v254, s15, 16
	v_writelane_b32 v254, s16, 17
	v_writelane_b32 v254, s17, 18
	v_writelane_b32 v254, s18, 19
	v_writelane_b32 v254, s19, 20
	s_load_dwordx16 s[4:19], s[0:1], 0xc0
	s_waitcnt lgkmcnt(0)
	v_writelane_b32 v254, s4, 21
	s_nop 1
	v_writelane_b32 v254, s5, 22
	v_writelane_b32 v254, s6, 23
	v_writelane_b32 v254, s7, 24
	v_writelane_b32 v254, s8, 25
	v_writelane_b32 v254, s9, 26
	v_writelane_b32 v254, s10, 27
	v_writelane_b32 v254, s11, 28
	v_writelane_b32 v254, s12, 29
	v_writelane_b32 v254, s13, 30
	v_writelane_b32 v254, s14, 31
	v_writelane_b32 v254, s15, 32
	v_writelane_b32 v254, s16, 33
	v_writelane_b32 v254, s17, 34
	v_writelane_b32 v254, s18, 35
	v_writelane_b32 v254, s19, 36
	v_writelane_b32 v254, s92, 37
	v_writelane_b32 v254, s64, 38
	s_nop 1
	v_writelane_b32 v254, s65, 39
	v_writelane_b32 v254, s66, 40
	v_writelane_b32 v254, s67, 41
	v_writelane_b32 v254, s39, 42
	v_writelane_b32 v254, s90, 43
	s_nop 1
	v_writelane_b32 v254, s91, 44
	v_writelane_b32 v254, s20, 45
	s_nop 1
	v_writelane_b32 v254, s21, 46
	v_writelane_b32 v254, s62, 47
	s_nop 1
	v_writelane_b32 v254, s63, 48
	v_writelane_b32 v254, s36, 49
	s_nop 1
	v_writelane_b32 v254, s37, 50
	v_writelane_b32 v254, s22, 51
	s_nop 1
	v_writelane_b32 v254, s23, 52
	v_writelane_b32 v254, s24, 53
	v_writelane_b32 v254, s88, 54
	s_nop 1
	v_writelane_b32 v254, s89, 55
	v_writelane_b32 v254, s30, 56
	s_nop 1
	v_writelane_b32 v254, s31, 57
	v_writelane_b32 v254, s34, 58
	s_nop 1
	v_writelane_b32 v254, s35, 59
	v_writelane_b32 v254, s40, 60
	s_nop 1
	v_writelane_b32 v255, s44, 0
	v_writelane_b32 v255, s45, 1
	v_writelane_b32 v255, s46, 2
	v_writelane_b32 v255, s47, 3
	v_writelane_b32 v255, s48, 4
	v_writelane_b32 v255, s49, 5
	v_writelane_b32 v255, s50, 6
	v_writelane_b32 v255, s51, 7
	v_writelane_b32 v255, s52, 8
	v_writelane_b32 v254, s41, 61
	v_writelane_b32 v255, s53, 9
	v_writelane_b32 v254, s42, 62
	v_writelane_b32 v255, s54, 10
	v_writelane_b32 v254, s43, 63
	v_writelane_b32 v255, s55, 11
	s_branch .LBB0_10

; #define LAS __attribute__((address_space(3)))
; __device__ __forceinline__ void ph_ret_fast(const Params& p, int jl, LAS unsigned char* lds, int tid, int lane, int wave) {
;     ...
;     const int fr = lane & 15, fq = lane >> 4, li_q = (lane & 15) >> 2, li_p = lane & 3;
;     for (int u = blockIdx.x; u < BATCH * RH * 8; u += gridDim.x) {
;         const int es = u & 7, h = (u >> 3) & 3, b = u >> 5;
;         const float gamma = 1.0f - exp2f(-5.0f - (float)h), lg = log2f(gamma), g128 = exp2f(128.f * lg), g127 = exp2f(127.f * lg);
;         const int it_ = wave < 4 ? wave : 11 - wave, i0 = 16 * it_, d0 = 32 * wave;
;         f32x4 Sacc[2][4];
; #pragma unroll
;         for (int a = 0; a < 2; ++a)
; #pragma unroll
;             for (int c = 0; c < 4; ++c) Sacc[a][c] = (f32x4){0.f, 0.f, 0.f, 0.f};
;         __syncthreads();
;         for (int i = tid; i < 64 * RT_SP / 16; i += NTHR) *(LAS v4u*)(lds + RT_ST_OFF + i * 16) = (v4u){0u, 0u, 0u, 0u};
;         v4u kst[8], vst[2];
;         const bf16* Kg = QK + 1024 + 256 * h; const bf16* Vg = V + 512 * h + 64 * es; const bf16* Qg = QK + 256 * h;
;     ...
;         RT_LOAD_STAGE(0);
;         bf16x8 Qf[8];
;     ...
;         RT_LOAD_Q(0);
;         for (int c = 0; c < 17; ++c) {
;             __syncthreads();
; #pragma unroll
;             for (int k_ = 0; k_ < 8; ++k_) { const int id_ = tid + 512 * k_, row_ = id_ >> 5, ch_ = id_ & 31; *(LAS v4u*)(lds + RT_K_OFF + row_ * RT_KP + ch_ * 16) = kst[k_]; }
; #pragma unroll
;             for (int k_ = 0; k_ < 2; ++k_) { const int id_ = tid + 512 * k_, row_ = id_ >> 3, ch_ = id_ & 7;
;                 float f[8]; unpack8(vst[k_], f); const float sc = exp2f(-(float)row_ * lg);
; #pragma unroll
;                 for (int e = 0; e < 8; ++e) f[e] *= sc;
;                 *(LAS v4u*)(lds + RT_V_OFF + row_ * RT_VP + ch_ * 16) = pack8(f); }
;             __syncthreads();
;             bf16x8 Pf[4];
;             { const int ii = i0 + fr; const float gi = exp2f((float)ii * lg);
; #pragma unroll
;               for (int s2 = 0; s2 < 4; ++s2) { f32x4 Dp[2];
;                   Dp[0] = (f32x4){0.f, 0.f, 0.f, 0.f}; Dp[1] = Dp[0];
;                   if (2 * s2 <= it_) {
;                       bf16x8 Ka[8], Kb[8];
; #pragma unroll
;                       for (int s = 0; s < 8; ++s) { Ka[s] = *(const LAS bf16x8*)(lds + RT_K_OFF + (16 * (2 * s2) + fr) * RT_KP + (32 * s + 8 * fq) * 2);
.LBB0_339:
	s_andn2_b64 vcc, exec, s[0:1]
	s_cbranch_vccnz .LBB0_464
	v_writelane_b32 v255, s46, 23
	v_writelane_b32 v255, s44, 16
	v_readlane_b32 s0, v252, 38
	v_readlane_b32 s1, v252, 39
	v_writelane_b32 v255, s45, 17
	v_writelane_b32 v255, s69, 25
	v_writelane_b32 v255, s68, 26
	v_writelane_b32 v255, s56, 18
	s_andn2_b64 vcc, exec, s[0:1]
	s_nop 0
	v_writelane_b32 v255, s57, 19
	s_cbranch_vccnz .LBB0_457
	v_readlane_b32 s2, v255, 15
	s_sub_i32 s0, 11, s2
	s_cmp_lt_i32 s2, 4
	s_cselect_b32 s0, s2, s0
	s_lshl_b32 s13, s0, 4
	s_movk_i32 s1, 0x840
	v_cmp_gt_i32_e64 s[4:5], s1, v194
	s_add_i32 s15, s13, 0xffffff90
	s_cmp_gt_i32 s0, 6
	v_writelane_b32 v255, s4, 27
	v_lshlrev_b32_e32 v8, 4, v194
	v_and_b32_e32 v3, 3, v194
	v_writelane_b32 v255, s5, 28
	s_cselect_b64 s[4:5], -1, 0
	s_waitcnt lgkmcnt(0)
	v_and_b32_e32 v2, 0x1f0, v8
	v_bfe_u32 v5, v194, 2, 2
	v_lshrrev_b32_e32 v4, 4, v238
	v_writelane_b32 v255, s4, 29
	v_add_u32_e32 v9, 0, v2
	v_and_b32_e32 v2, 0x70, v8
	v_readlane_b32 s1, v253, 63
	v_lshlrev_b32_e32 v14, 3, v3
	v_writelane_b32 v255, s5, 30
	v_add_u32_e32 v10, s1, v2
	v_lshlrev_b32_e32 v12, 2, v4
	v_add_u32_e32 v165, s1, v14
	v_lshl_or_b32 v15, v4, 3, v5
	v_mov_b32_e32 v4, s1
	s_movk_i32 s1, 0x90
	v_and_b32_e32 v0, 15, v194
	v_mad_u32_u24 v17, v15, s1, v4
	v_lshl_or_b32 v4, s2, 5, v12
	v_readlane_b32 s2, v255, 25
	v_or_b32_e32 v11, s13, v0
	s_lshl_b32 s2, s2, 3
	v_writelane_b32 v255, s2, 31
	v_cmp_lt_i32_e64 s[2:3], v11, v12
	s_waitcnt vmcnt(0)
	v_or_b32_e32 v28, 2, v12
	v_or_b32_e32 v29, 33, v12
	v_writelane_b32 v255, s2, 32
	s_waitcnt vmcnt(2)
	v_or_b32_e32 v30, 0x41, v12
	s_waitcnt lgkmcnt(0)
	v_cmp_lt_i32_e64 s[28:29], v11, v29
	v_writelane_b32 v255, s3, 33
	v_cmp_gt_i32_e64 s[2:3], v11, v12
	v_or_b32_e32 v29, 34, v12
	v_cmp_lt_i32_e64 s[46:47], v11, v30
	v_writelane_b32 v255, s2, 34
	v_or_b32_e32 v30, 0x42, v12
	v_or_b32_e32 v6, s13, v12
	v_writelane_b32 v255, s3, 35
	v_cmp_lt_i32_e64 s[2:3], v11, v28
	v_or_b32_e32 v28, 3, v12
	v_cmp_lt_i32_e64 s[16:17], v11, v28
	v_or_b32_e32 v28, 16, v12
	v_cmp_lt_i32_e64 s[30:31], v11, v29
	v_or_b32_e32 v29, 35, v12
	v_cmp_lt_i32_e64 s[48:49], v11, v30
	v_or_b32_e32 v30, 0x43, v12
	v_or_b32_e32 v7, 1, v6
	v_cmp_lt_i32_e64 s[18:19], v11, v28
	v_or_b32_e32 v28, 17, v12
	v_cmp_lt_i32_e64 s[34:35], v11, v29
	v_or_b32_e32 v29, 48, v12
	v_cmp_lt_i32_e64 s[50:51], v11, v30
	v_or_b32_e32 v30, 0x50, v12
	v_cmp_lt_i32_e64 s[20:21], v11, v28
	v_or_b32_e32 v28, 18, v12
	v_cmp_lt_i32_e64 s[36:37], v11, v29
	v_or_b32_e32 v29, 49, v12
	v_cmp_lt_i32_e64 s[52:53], v11, v30
	v_or_b32_e32 v30, 0x51, v12
	v_cvt_f32_i32_e32 v170, v7
	v_or_b32_e32 v7, 2, v6
	v_cmp_lt_i32_e64 s[22:23], v11, v28
	v_or_b32_e32 v28, 19, v12
	v_cmp_lt_i32_e64 s[38:39], v11, v29
	v_or_b32_e32 v29, 50, v12
	v_cmp_lt_i32_e64 s[54:55], v11, v30
	v_or_b32_e32 v30, 0x52, v12
	v_cvt_f32_i32_e32 v171, v7
	v_or_b32_e32 v7, 3, v6
	v_add_u32_e32 v6, 4, v6
	v_cmp_lt_i32_e64 s[24:25], v11, v28
	v_or_b32_e32 v28, 32, v12
	v_cmp_lt_i32_e64 s[40:41], v11, v29
	v_or_b32_e32 v29, 51, v12
	v_cmp_lt_i32_e64 s[56:57], v11, v30
	v_or_b32_e32 v30, 0x53, v12
	v_cvt_f32_i32_e32 v173, v6
	v_or_b32_e32 v6, v12, v5
	v_cmp_lt_i32_e64 s[42:43], v11, v29
	v_or_b32_e32 v29, 64, v12
	v_cmp_lt_i32_e64 s[58:59], v11, v30
	v_or_b32_e32 v30, 0x60, v12
	v_mul_u32_u24_e32 v174, 0x90, v6
	v_or_b32_e32 v6, v28, v5
	v_mul_u32_u24_e32 v175, 0x90, v6
	v_or_b32_e32 v6, v29, v5
	v_or_b32_e32 v5, v30, v5
	v_mul_u32_u24_e32 v177, 0x90, v5
	v_or_b32_e32 v5, 32, v15
	v_mul_u32_u24_e32 v176, 0x90, v6
	v_mul_u32_u24_e32 v6, 0x210, v5
	v_add3_u32 v178, 0, v6, v14
	v_or_b32_e32 v6, 48, v238
	v_mul_u32_u24_e32 v180, 0x210, v6
	v_or_b32_e32 v6, 1, v4
	s_waitcnt vmcnt(1)
	v_add_u32_e32 v19, 0x200, v194
	v_cvt_f32_i32_e32 v172, v7
	v_ashrrev_i32_e32 v7, 31, v6
	v_ashrrev_i32_e32 v20, 5, v19
	v_ashrrev_i32_e32 v27, 3, v194
	v_ashrrev_i32_e32 v19, 3, v19
	s_cmp_gt_i32 s0, -1
	v_lshlrev_b64 v[100:101], 11, v[6:7]
	v_or_b32_e32 v6, 2, v4
	v_add_u32_e32 v21, 0x400, v194
	s_waitcnt vmcnt(0)
; #define LAS __attribute__((address_space(3)))
; __device__ __forceinline__ void unpack8(const v4u w, float (&f)[8]) { f[0] = bf_lo(w.x); f[1] = bf_hi(w.x); f[2] = bf_lo(w.y); f[3] = bf_hi(w.y); f[4] = bf_lo(w.z); f[5] = bf_hi(w.z); f[6] = bf_lo(w.w); f[7] = bf_hi(w.w); }
; __device__ __forceinline__ void ph_ret_fast(const Params& p, int jl, LAS unsigned char* lds, int tid, int lane, int wave) {
;     ...
;         const int it_ = wave < 4 ? wave : 11 - wave, i0 = 16 * it_, d0 = 32 * wave;
;         f32x4 Sacc[2][4];
; #pragma unroll
;         for (int a = 0; a < 2; ++a)
; #pragma unroll
;             for (int c = 0; c < 4; ++c) Sacc[a][c] = (f32x4){0.f, 0.f, 0.f, 0.f};
;         __syncthreads();
;         for (int i = tid; i < 64 * RT_SP / 16; i += NTHR) *(LAS v4u*)(lds + RT_ST_OFF + i * 16) = (v4u){0u, 0u, 0u, 0u};
;         v4u kst[8], vst[2];
;         const bf16* Kg = QK + 1024 + 256 * h; const bf16* Vg = V + 512 * h + 64 * es; const bf16* Qg = QK + 256 * h;
;     ...
;         RT_LOAD_STAGE(0);
;         bf16x8 Qf[8];
;     ...
;         RT_LOAD_Q(0);
;         for (int c = 0; c < 17; ++c) {
;             __syncthreads();
; #pragma unroll
;             for (int k_ = 0; k_ < 8; ++k_) { const int id_ = tid + 512 * k_, row_ = id_ >> 5, ch_ = id_ & 31; *(LAS v4u*)(lds + RT_K_OFF + row_ * RT_KP + ch_ * 16) = kst[k_]; }
; #pragma unroll
;             for (int k_ = 0; k_ < 2; ++k_) { const int id_ = tid + 512 * k_, row_ = id_ >> 3, ch_ = id_ & 7;
;                 float f[8]; unpack8(vst[k_], f); const float sc = exp2f(-(float)row_ * lg);
; #pragma unroll
;                 for (int e = 0; e < 8; ++e) f[e] *= sc;
;                 *(LAS v4u*)(lds + RT_V_OFF + row_ * RT_VP + ch_ * 16) = pack8(f); }
;             __syncthreads();
;             bf16x8 Pf[4];
;             { const int ii = i0 + fr; const float gi = exp2f((float)ii * lg);
; #pragma unroll
;               for (int s2 = 0; s2 < 4; ++s2) { f32x4 Dp[2];
;                   Dp[0] = (f32x4){0.f, 0.f, 0.f, 0.f}; Dp[1] = Dp[0];
;                   if (2 * s2 <= it_) {
;                       bf16x8 Ka[8], Kb[8];
; #pragma unroll
;                       for (int s = 0; s < 8; ++s) { Ka[s] = *(const LAS bf16x8*)(lds + RT_K_OFF + (16 * (2 * s2) + fr) * RT_KP + (32 * s + 8 * fq) * 2);
;                           Kb[s] = *(const LAS bf16x8*)(lds + RT_K_OFF + (16 * (2 * s2 + 1) + fr) * RT_KP + (32 * s + 8 * fq) * 2); }
	v_add_u32_e32 v22, 0x600, v194
	v_add_u32_e32 v23, 0x800, v194
	v_add_u32_e32 v24, 0xa00, v194
	v_add_u32_e32 v25, 0xc00, v194
	v_add_u32_e32 v26, 0xe00, v194
	v_cvt_f32_i32_e32 v166, v27
	v_mul_lo_u32 v27, v27, s1
	v_cvt_f32_i32_e32 v167, v19
	v_mul_lo_u32 v19, v19, s1
	s_cselect_b64 s[4:5], -1, 0
	v_writelane_b32 v255, s2, 36
	s_cmp_gt_i32 s0, 1
	v_readlane_b32 s1, v254, 0
	v_ashrrev_i32_e32 v7, 31, v6
	v_ashrrev_i32_e32 v18, 5, v194
	s_movk_i32 s12, 0x210
	v_ashrrev_i32_e32 v21, 5, v21
	v_ashrrev_i32_e32 v22, 5, v22
	v_ashrrev_i32_e32 v23, 5, v23
	v_ashrrev_i32_e32 v24, 5, v24
	v_ashrrev_i32_e32 v25, 5, v25
	v_ashrrev_i32_e32 v26, 5, v26
	v_writelane_b32 v255, s3, 37
	s_cselect_b64 s[2:3], -1, 0
	s_cmp_gt_i32 s0, 3
	v_mov_b32_e32 v32, s1
	v_mov_b32_e32 v33, 0x4200
	v_lshlrev_b64 v[102:103], 11, v[6:7]
	v_or_b32_e32 v6, 3, v4
	v_mul_lo_u32 v18, v18, s12
	v_mul_lo_u32 v20, v20, s12
	v_mul_lo_u32 v21, v21, s12
	v_mul_lo_u32 v22, v22, s12
	v_mul_lo_u32 v23, v23, s12
	v_mul_lo_u32 v24, v24, s12
	v_mul_lo_u32 v25, v25, s12
	v_mul_lo_u32 v26, v26, s12
	s_cselect_b64 s[92:93], -1, 0
	s_cmp_gt_i32 s0, 5
	v_or_b32_e32 v31, 0x61, v12
	v_mad_u32_u24 v32, v0, s12, v32
	v_mad_u32_u24 v33, v0, s12, v33
	v_readlane_b32 s12, v255, 13
	v_ashrrev_i32_e32 v7, 31, v6
	s_cselect_b64 s[84:85], -1, 0
	v_cmp_lt_i32_e64 s[62:63], v11, v31
	v_or_b32_e32 v31, 0x62, v12
	s_and_b32 s27, s12, 0xffffffc0
	v_lshlrev_b64 v[104:105], 11, v[6:7]
	v_or_b32_e32 v6, 16, v4
	v_cmp_lt_i32_e64 s[64:65], v11, v31
	v_or_b32_e32 v31, 0x63, v12
	v_ashrrev_i32_e32 v7, 31, v6
	s_cmpk_gt_i32 s0, 0xff86
	v_mul_u32_u24_e32 v16, 0x210, v15
	v_cmp_lt_i32_e64 s[66:67], v11, v31
	v_or_b32_e32 v31, 0x70, v12
	v_mul_u32_u24_e32 v15, 0x90, v5
	v_lshlrev_b32_e32 v5, 1, v4
	v_readlane_b32 s12, v254, 1
	v_lshlrev_b64 v[106:107], 11, v[6:7]
	v_or_b32_e32 v6, 17, v4
	s_cselect_b64 s[74:75], -1, 0
	v_cvt_f32_i32_e32 v164, v11
	v_cmp_lt_i32_e64 s[68:69], v11, v31
	v_or_b32_e32 v31, 0x71, v12
	v_add_u32_e32 v179, s1, v5
	v_add_u32_e32 v181, s12, v5
	v_ashrrev_i32_e32 v5, 31, v4
	v_ashrrev_i32_e32 v7, 31, v6
	v_writelane_b32 v255, s74, 21
	v_and_b32_e32 v13, 48, v194
	v_and_b32_e32 v2, 1, v194
	v_cmp_lt_i32_e64 s[70:71], v11, v31
	v_or_b32_e32 v31, 0x72, v12
	v_lshlrev_b64 v[98:99], 11, v[4:5]
	v_lshlrev_b64 v[108:109], 11, v[6:7]
	v_or_b32_e32 v6, 18, v4
	v_or_b32_e32 v4, 19, v4
	v_writelane_b32 v255, s75, 22
	s_add_i32 s0, s13, 0x790
	v_cmp_eq_u32_e64 s[6:7], 0, v2
	v_and_b32_e32 v2, 12, v194
	v_mul_u32_u24_e32 v168, 0x210, v0
	v_cmp_lt_i32_e64 s[10:11], v11, v28
	v_cmp_lt_i32_e64 s[44:45], v11, v29
	v_cmp_lt_i32_e64 s[72:73], v11, v31
	v_or_b32_e32 v31, 0x73, v12
	v_add_u32_e32 v34, s1, v33
	v_add_u32_e32 v35, s1, v13
	v_add3_u32 v16, 0, v16, v14
	v_add_u32_e32 v28, 0x4200, v178
	v_add_u32_e32 v29, 0x8400, v178
	v_ashrrev_i32_e32 v7, 31, v6
	v_ashrrev_i32_e32 v5, 31, v4
	v_or_b32_e32 v182, v12, v3
	v_writelane_b32 v255, s0, 38
	v_readlane_b32 s0, v254, 37
	v_cmp_gt_u32_e64 s[8:9], 2, v3
	v_add3_u32 v169, 0, v168, v13
	v_cmp_lt_i32_e64 s[60:61], v11, v30
	v_lshlrev_b64 v[110:111], 11, v[6:7]
	v_lshlrev_b64 v[112:113], 11, v[4:5]
	s_mov_b32 s14, s13
	v_add_u32_e32 v183, 0xfffffe00, v194
	v_add_u32_e32 v184, s1, v8
	v_writelane_b32 v255, s15, 40
	v_or_b32_e32 v185, s15, v182
	v_lshlrev_b32_e32 v114, 1, v2
	v_lshlrev_b32_e32 v116, 2, v0
	v_add_u32_e32 v186, v9, v18
	v_add_u32_e32 v187, v9, v20
	v_add_u32_e32 v188, v9, v21
	v_add_u32_e32 v189, v9, v22
	v_add_u32_e32 v190, v9, v23
	v_add_u32_e32 v191, v9, v24
	v_add_u32_e32 v192, v9, v25
	v_add_u32_e32 v193, v9, v26
	v_add_u32_e32 v195, v10, v27
	v_add_u32_e32 v196, v10, v19
	v_add_u32_e32 v197, v32, v13
	v_add_u32_e32 v198, v35, v33
	v_add_u32_e32 v199, v34, v13
	v_add_u32_e32 v200, s27, v16
	v_add_u32_e32 v201, v17, v14
	v_add_u32_e32 v202, v165, v15
	v_add_u32_e32 v203, s27, v28
	s_mov_b32 s15, s27
	v_add_u32_e32 v204, s27, v29
	s_and_b32 s100, s0, 7
	s_lshl_b32 s100, s100, 5
	s_lshr_b32 s13, s0, 3
	s_or_b32 s13, s13, s100
	v_cmp_lt_i32_e64 s[74:75], v11, v31
	s_branch .LBB0_343

; #define LAS __attribute__((address_space(3)))
; __device__ __forceinline__ void unpack8(const v4u w, float (&f)[8]) { f[0] = bf_lo(w.x); f[1] = bf_hi(w.x); f[2] = bf_lo(w.y); f[3] = bf_hi(w.y); f[4] = bf_lo(w.z); f[5] = bf_hi(w.z); f[6] = bf_lo(w.w); f[7] = bf_hi(w.w); }
; __device__ __forceinline__ v4u pack8(const float (&f)[8]) { v4u w; w.x = cvt_pk_bf16(f[0], f[1]); w.y = cvt_pk_bf16(f[2], f[3]); w.z = cvt_pk_bf16(f[4], f[5]); w.w = cvt_pk_bf16(f[6], f[7]); return w; }
; __device__ __forceinline__ void ph_ret_fast(const Params& p, int jl, LAS unsigned char* lds, int tid, int lane, int wave) {
;     ...
;         const float gamma = 1.0f - exp2f(-5.0f - (float)h), lg = log2f(gamma), g128 = exp2f(128.f * lg), g127 = exp2f(127.f * lg);
;         const int it_ = wave < 4 ? wave : 11 - wave, i0 = 16 * it_, d0 = 32 * wave;
;         f32x4 Sacc[2][4];
; #pragma unroll
;         for (int a = 0; a < 2; ++a)
; #pragma unroll
;             for (int c = 0; c < 4; ++c) Sacc[a][c] = (f32x4){0.f, 0.f, 0.f, 0.f};
;         __syncthreads();
;         for (int i = tid; i < 64 * RT_SP / 16; i += NTHR) *(LAS v4u*)(lds + RT_ST_OFF + i * 16) = (v4u){0u, 0u, 0u, 0u};
;         v4u kst[8], vst[2];
;         const bf16* Kg = QK + 1024 + 256 * h; const bf16* Vg = V + 512 * h + 64 * es; const bf16* Qg = QK + 256 * h;
;     ...
;         RT_LOAD_STAGE(0);
;         bf16x8 Qf[8];
;     ...
;         RT_LOAD_Q(0);
;         for (int c = 0; c < 17; ++c) {
;             __syncthreads();
; #pragma unroll
;             for (int k_ = 0; k_ < 8; ++k_) { const int id_ = tid + 512 * k_, row_ = id_ >> 5, ch_ = id_ & 31; *(LAS v4u*)(lds + RT_K_OFF + row_ * RT_KP + ch_ * 16) = kst[k_]; }
; #pragma unroll
;             for (int k_ = 0; k_ < 2; ++k_) { const int id_ = tid + 512 * k_, row_ = id_ >> 3, ch_ = id_ & 7;
;                 float f[8]; unpack8(vst[k_], f); const float sc = exp2f(-(float)row_ * lg);
; #pragma unroll
;                 for (int e = 0; e < 8; ++e) f[e] *= sc;
;                 *(LAS v4u*)(lds + RT_V_OFF + row_ * RT_VP + ch_ * 16) = pack8(f); }
;             __syncthreads();
;             bf16x8 Pf[4];
;             { const int ii = i0 + fr; const float gi = exp2f((float)ii * lg);
;     ...
;             for (int r = 0; r < 4; ++r) { const float lam = exp2f((float)(i0 + 4 * fq + r + 1) * lg);
; #pragma unroll
;                 for (int et = 0; et < 4; ++et) Oacc[et][r] *= lam; }
.LBB0_383:
	s_lshl_b32 s0, s12, 1
	v_readlane_b32 s12, v252, 54
	v_readlane_b32 s13, v252, 55
	s_add_u32 s0, s12, s0
	s_addc_u32 s1, s13, 0
	s_add_u32 s0, s0, s76
	v_mul_f32_e32 v0, v76, v164
	s_mov_b32 s76, 0xc2fc0000
	v_cmp_gt_f32_e32 vcc, s76, v0
	v_div_scale_f32 v75, s[12:13], v118, v118, v77
	s_nop 0
	v_cndmask_b32_e32 v74, 0, v227, vcc
	v_fmac_f32_e32 v74, v76, v164
	v_exp_f32_e32 v74, v74
	v_rcp_f32_e32 v78, v75
	v_cndmask_b32_e32 v0, 0, v228, vcc
	s_addc_u32 s1, s1, 0
	v_ldexp_f32 v117, v74, v0
	v_fma_f32 v0, -v75, v78, 1.0
	v_fmac_f32_e32 v78, v0, v78
	v_div_scale_f32 v0, vcc, v77, v118, v77
	v_mul_f32_e32 v74, v0, v78
	v_fma_f32 v79, -v75, v74, v0
	v_fmac_f32_e32 v74, v79, v78
	v_fma_f32 v0, -v75, v74, v0
	v_div_fmas_f32 v0, v0, v78, v74
	v_div_fixup_f32 v122, v0, v118, v77
	v_mul_f32_e64 v0, v76, -v166
	v_cmp_gt_f32_e32 vcc, s76, v0
	v_mul_f32_e64 v75, v76, -v167
	v_mov_b32_e32 v115, v1
	v_cndmask_b32_e32 v0, 0, v228, vcc
	v_cndmask_b32_e32 v74, 0, v227, vcc
	v_cmp_gt_f32_e32 vcc, s76, v75
	v_fma_f32 v74, v76, -v166, v74
	v_exp_f32_e32 v74, v74
	v_cndmask_b32_e32 v77, 0, v227, vcc
	v_fma_f32 v77, v76, -v167, v77
	v_exp_f32_e32 v77, v77
	v_cndmask_b32_e32 v75, 0, v228, vcc
	v_ldexp_f32 v205, v74, v0
	v_mul_f32_e32 v0, v76, v170
	v_lshl_add_u64 v[126:127], s[0:1], 0, v[114:115]
	v_ldexp_f32 v115, v77, v75
	v_cmp_gt_f32_e32 vcc, s76, v0
	v_mul_f32_e32 v75, v76, v171
	v_mul_f32_e32 v78, v76, v172
	v_cndmask_b32_e32 v0, 0, v228, vcc
	v_cndmask_b32_e32 v74, 0, v227, vcc
	v_cmp_gt_f32_e32 vcc, s76, v75
	v_mul_f32_e32 v80, v76, v173
	v_fmac_f32_e32 v74, v76, v170
	v_cndmask_b32_e32 v75, 0, v228, vcc
	v_cndmask_b32_e32 v77, 0, v227, vcc
	v_cmp_gt_f32_e32 vcc, s76, v78
	v_fmac_f32_e32 v77, v76, v171
	v_exp_f32_e32 v74, v74
	v_cndmask_b32_e32 v78, 0, v228, vcc
	v_cndmask_b32_e32 v79, 0, v227, vcc
	v_cmp_gt_f32_e32 vcc, s76, v80
	v_fmac_f32_e32 v79, v76, v172
	v_exp_f32_e32 v77, v77
	v_cndmask_b32_e32 v81, 0, v227, vcc
	v_fmac_f32_e32 v81, v76, v173
	v_exp_f32_e32 v79, v79
	v_exp_f32_e32 v76, v81
	v_cndmask_b32_e32 v80, 0, v228, vcc
	v_mov_b32_e32 v124, v122
	v_mov_b32_e32 v125, v122
	v_mov_b32_e32 v120, v118
	v_mov_b32_e32 v121, v118
	v_ldexp_f32 v130, v74, v0
	v_ldexp_f32 v131, v77, v75
	v_ldexp_f32 v134, v79, v78
	v_ldexp_f32 v135, v76, v80
	v_add_u32_e32 v206, s94, v185
	s_add_i32 s12, s14, s94
	v_mov_b32_e32 v129, v128
	v_mov_b32_e32 v132, v128
	v_mov_b32_e32 v133, v128
	v_mov_b32_e32 v136, v128
	v_mov_b32_e32 v137, v128
	v_mov_b32_e32 v138, v128
	v_mov_b32_e32 v139, v128
	v_mov_b32_e32 v140, v128
	v_mov_b32_e32 v141, v128
	v_mov_b32_e32 v142, v128
	v_mov_b32_e32 v143, v128
	v_mov_b32_e32 v144, v128
	v_mov_b32_e32 v145, v128
	v_mov_b32_e32 v146, v128
	v_mov_b32_e32 v147, v128
	v_mov_b32_e32 v152, v128
	v_mov_b32_e32 v153, v128
	v_mov_b32_e32 v158, v128
	v_mov_b32_e32 v159, v128
	v_mov_b32_e32 v148, v128
	v_mov_b32_e32 v149, v128
	v_mov_b32_e32 v150, v128
	v_mov_b32_e32 v151, v128
	v_mov_b32_e32 v154, v128
	v_mov_b32_e32 v155, v128
	v_mov_b32_e32 v156, v128
	v_mov_b32_e32 v157, v128
	v_mov_b32_e32 v160, v128
	v_mov_b32_e32 v161, v128
	v_mov_b32_e32 v162, v128
	v_mov_b32_e32 v163, v128
	s_waitcnt vmcnt(0)
	s_branch .LBB0_386

; #define LAS __attribute__((address_space(3)))
; __device__ __forceinline__ void unpack8(const v4u w, float (&f)[8]) { f[0] = bf_lo(w.x); f[1] = bf_hi(w.x); f[2] = bf_lo(w.y); f[3] = bf_hi(w.y); f[4] = bf_lo(w.z); f[5] = bf_hi(w.z); f[6] = bf_lo(w.w); f[7] = bf_hi(w.w); }
; __device__ __forceinline__ v4u pack8(const float (&f)[8]) { v4u w; w.x = cvt_pk_bf16(f[0], f[1]); w.y = cvt_pk_bf16(f[2], f[3]); w.z = cvt_pk_bf16(f[4], f[5]); w.w = cvt_pk_bf16(f[6], f[7]); return w; }
; __device__ __forceinline__ void ph_ret_fast(const Params& p, int jl, LAS unsigned char* lds, int tid, int lane, int wave) {
;     ...
;             __syncthreads();
; #pragma unroll
;             for (int k_ = 0; k_ < 8; ++k_) { const int id_ = tid + 512 * k_, row_ = id_ >> 5, ch_ = id_ & 31; *(LAS v4u*)(lds + RT_K_OFF + row_ * RT_KP + ch_ * 16) = kst[k_]; }
; #pragma unroll
;             for (int k_ = 0; k_ < 2; ++k_) { const int id_ = tid + 512 * k_, row_ = id_ >> 3, ch_ = id_ & 7;
;                 float f[8]; unpack8(vst[k_], f); const float sc = exp2f(-(float)row_ * lg);
; #pragma unroll
;                 for (int e = 0; e < 8; ++e) f[e] *= sc;
;                 *(LAS v4u*)(lds + RT_V_OFF + row_ * RT_VP + ch_ * 16) = pack8(f); }
;             __syncthreads();
;             bf16x8 Pf[4];
;             { const int ii = i0 + fr; const float gi = exp2f((float)ii * lg);
; #pragma unroll
;               for (int s2 = 0; s2 < 4; ++s2) { f32x4 Dp[2];
;                   Dp[0] = (f32x4){0.f, 0.f, 0.f, 0.f}; Dp[1] = Dp[0];
;                   if (2 * s2 <= it_) {
;                       bf16x8 Ka[8], Kb[8];
; #pragma unroll
;                       for (int s = 0; s < 8; ++s) { Ka[s] = *(const LAS bf16x8*)(lds + RT_K_OFF + (16 * (2 * s2) + fr) * RT_KP + (32 * s + 8 * fq) * 2);
;                           Kb[s] = *(const LAS bf16x8*)(lds + RT_K_OFF + (16 * (2 * s2 + 1) + fr) * RT_KP + (32 * s + 8 * fq) * 2); }
;                       __builtin_amdgcn_sched_barrier(0);
;                       __builtin_amdgcn_s_setprio(1);
; #pragma unroll
;                       for (int s = 0; s < 8; ++s) { Dp[0] = __builtin_amdgcn_mfma_f32_16x16x32_bf16(Ka[s], Qf[s], Dp[0], 0, 0, 0); Dp[1] = __builtin_amdgcn_mfma_f32_16x16x32_bf16(Kb[s], Qf[s], Dp[1], 0, 0, 0); }
;                       __builtin_amdgcn_s_setprio(0);
;                       __builtin_amdgcn_sched_barrier(0);
;                   }
.LBB0_386:
	s_waitcnt lgkmcnt(0)
	s_barrier
	s_waitcnt vmcnt(8)
	ds_write_b128 v186, v[2:5]
	ds_write_b128 v187, v[6:9]
	ds_write_b128 v188, v[10:13]
	ds_write_b128 v189, v[14:17]
	ds_write_b128 v190, v[18:21]
	ds_write_b128 v191, v[22:25]
	ds_write_b128 v192, v[26:29]
	ds_write_b128 v193, v[34:37]
	v_and_b32_e32 v2, 0xffff0000, v46
	v_lshlrev_b32_e32 v0, 16, v46
	v_lshlrev_b32_e32 v3, 16, v47
	v_and_b32_e32 v4, 0xffff0000, v47
	v_lshlrev_b32_e32 v5, 16, v48
	v_mul_f32_e32 v2, v205, v2
	v_and_b32_e32 v6, 0xffff0000, v48
	v_lshlrev_b32_e32 v7, 16, v49
	v_and_b32_e32 v8, 0xffff0000, v49
	v_mul_f32_e32 v0, v205, v0
	v_mul_f32_e32 v3, v205, v3
	v_mul_f32_e32 v4, v205, v4
	v_mul_f32_e32 v5, v205, v5
	v_cvt_pk_bf16_f32 v2, v0, v2
	v_mul_f32_e32 v6, v205, v6
	v_mul_f32_e32 v7, v205, v7
	v_mul_f32_e32 v8, v205, v8
	v_cvt_pk_bf16_f32 v3, v3, v4
	v_cvt_pk_bf16_f32 v4, v5, v6
	v_cvt_pk_bf16_f32 v5, v7, v8
	ds_write_b128 v195, v[2:5]
	v_lshlrev_b32_e32 v0, 16, v50
	v_and_b32_e32 v2, 0xffff0000, v50
	v_lshlrev_b32_e32 v3, 16, v51
	v_and_b32_e32 v4, 0xffff0000, v51
	v_lshlrev_b32_e32 v5, 16, v52
	v_and_b32_e32 v6, 0xffff0000, v52
	v_lshlrev_b32_e32 v7, 16, v53
	v_and_b32_e32 v8, 0xffff0000, v53
	v_mul_f32_e32 v0, v115, v0
	v_mul_f32_e32 v2, v115, v2
	v_mul_f32_e32 v3, v115, v3
	v_mul_f32_e32 v4, v115, v4
	v_mul_f32_e32 v5, v115, v5
	v_mul_f32_e32 v6, v115, v6
	v_mul_f32_e32 v7, v115, v7
	v_mul_f32_e32 v8, v115, v8
	v_cvt_pk_bf16_f32 v2, v0, v2
	v_cndmask_b32_e64 v0, 0, 1, s[4:5]
	v_cvt_pk_bf16_f32 v3, v3, v4
	v_cvt_pk_bf16_f32 v4, v5, v6
	v_cvt_pk_bf16_f32 v5, v7, v8
	v_cmp_ne_u32_e64 s[76:77], 1, v0
	s_andn2_b64 vcc, exec, s[4:5]
	v_mov_b32_e32 v6, 0
	v_mov_b32_e32 v7, 0
	v_mov_b32_e32 v8, 0
	v_mov_b32_e32 v9, 0
	v_mov_b32_e32 v10, 0
	v_mov_b32_e32 v11, 0
	v_mov_b32_e32 v12, 0
	v_mov_b32_e32 v13, 0
	ds_write_b128 v196, v[2:5]
	s_waitcnt lgkmcnt(0)
	s_barrier
	s_waitcnt vmcnt(0)
	s_cbranch_vccnz .LBB0_388
	ds_read_b128 v[2:5], v169
	ds_read_b128 v[6:9], v169 offset:64
	ds_read_b128 v[10:13], v169 offset:8448
	ds_read_b128 v[14:17], v169 offset:8512
	ds_read_b128 v[18:21], v169 offset:128
	ds_read_b128 v[22:25], v169 offset:192
	ds_read_b128 v[26:29], v169 offset:8576
	ds_read_b128 v[34:37], v169 offset:8640
	ds_read_b128 v[46:49], v169 offset:256
	ds_read_b128 v[50:53], v169 offset:320
	ds_read_b128 v[74:77], v169 offset:8704
	ds_read_b128 v[78:81], v169 offset:8768
	ds_read_b128 v[82:85], v169 offset:384
	ds_read_b128 v[86:89], v169 offset:448
	ds_read_b128 v[90:93], v169 offset:8832
	ds_read_b128 v[94:97], v169 offset:8896
	s_setprio 1
	s_waitcnt lgkmcnt(14)
	v_mfma_f32_16x16x32_bf16 v[2:5], v[2:5], v[30:33], 0
	s_waitcnt lgkmcnt(13)
	v_mfma_f32_16x16x32_bf16 v[10:13], v[10:13], v[30:33], 0
	v_mfma_f32_16x16x32_bf16 v[2:5], v[6:9], v[38:41], v[2:5]
	s_waitcnt lgkmcnt(12)
	v_mfma_f32_16x16x32_bf16 v[6:9], v[14:17], v[38:41], v[10:13]
	s_waitcnt lgkmcnt(11)
	v_mfma_f32_16x16x32_bf16 v[2:5], v[18:21], v[42:45], v[2:5]
	s_waitcnt lgkmcnt(9)
	v_mfma_f32_16x16x32_bf16 v[6:9], v[26:29], v[42:45], v[6:9]
	v_mfma_f32_16x16x32_bf16 v[2:5], v[22:25], v[54:57], v[2:5]
	s_waitcnt lgkmcnt(8)
	v_mfma_f32_16x16x32_bf16 v[6:9], v[34:37], v[54:57], v[6:9]
	s_waitcnt lgkmcnt(7)
	v_mfma_f32_16x16x32_bf16 v[2:5], v[46:49], v[58:61], v[2:5]
	s_waitcnt lgkmcnt(5)
	v_mfma_f32_16x16x32_bf16 v[6:9], v[74:77], v[58:61], v[6:9]
	v_mfma_f32_16x16x32_bf16 v[2:5], v[50:53], v[62:65], v[2:5]
	s_waitcnt lgkmcnt(4)
	v_mfma_f32_16x16x32_bf16 v[6:9], v[78:81], v[62:65], v[6:9]
	s_waitcnt lgkmcnt(3)
	v_mfma_f32_16x16x32_bf16 v[2:5], v[82:85], v[66:69], v[2:5]
	s_waitcnt lgkmcnt(1)
	v_mfma_f32_16x16x32_bf16 v[6:9], v[90:93], v[66:69], v[6:9]
	v_mfma_f32_16x16x32_bf16 v[10:13], v[86:89], v[70:73], v[2:5]
	s_waitcnt lgkmcnt(0)
	v_mfma_f32_16x16x32_bf16 v[6:9], v[94:97], v[70:73], v[6:9]
	s_setprio 0

; #define LAS __attribute__((address_space(3)))
; __device__ __forceinline__ void unpack8(const v4u w, float (&f)[8]) { f[0] = bf_lo(w.x); f[1] = bf_hi(w.x); f[2] = bf_lo(w.y); f[3] = bf_hi(w.y); f[4] = bf_lo(w.z); f[5] = bf_hi(w.z); f[6] = bf_lo(w.w); f[7] = bf_hi(w.w); }
; __device__ __forceinline__ v4u pack8(const float (&f)[8]) { v4u w; w.x = cvt_pk_bf16(f[0], f[1]); w.y = cvt_pk_bf16(f[2], f[3]); w.z = cvt_pk_bf16(f[4], f[5]); w.w = cvt_pk_bf16(f[6], f[7]); return w; }
; __device__ __forceinline__ void ph_ret_fast(const Params& p, int jl, LAS unsigned char* lds, int tid, int lane, int wave) {
;     ...
;             __syncthreads();
; #pragma unroll
;             for (int k_ = 0; k_ < 8; ++k_) { const int id_ = tid + 512 * k_, row_ = id_ >> 5, ch_ = id_ & 31; *(LAS v4u*)(lds + RT_K_OFF + row_ * RT_KP + ch_ * 16) = kst[k_]; }
; #pragma unroll
;             for (int k_ = 0; k_ < 2; ++k_) { const int id_ = tid + 512 * k_, row_ = id_ >> 3, ch_ = id_ & 7;
;                 float f[8]; unpack8(vst[k_], f); const float sc = exp2f(-(float)row_ * lg);
; #pragma unroll
;                 for (int e = 0; e < 8; ++e) f[e] *= sc;
;                 *(LAS v4u*)(lds + RT_V_OFF + row_ * RT_VP + ch_ * 16) = pack8(f); }
;             __syncthreads();
;             bf16x8 Pf[4];
;             { const int ii = i0 + fr; const float gi = exp2f((float)ii * lg);
; #pragma unroll
;               for (int s2 = 0; s2 < 4; ++s2) { f32x4 Dp[2];
;                   Dp[0] = (f32x4){0.f, 0.f, 0.f, 0.f}; Dp[1] = Dp[0];
;                   if (2 * s2 <= it_) {
;                       bf16x8 Ka[8], Kb[8];
; #pragma unroll
;                       for (int s = 0; s < 8; ++s) { Ka[s] = *(const LAS bf16x8*)(lds + RT_K_OFF + (16 * (2 * s2) + fr) * RT_KP + (32 * s + 8 * fq) * 2);
;                           Kb[s] = *(const LAS bf16x8*)(lds + RT_K_OFF + (16 * (2 * s2 + 1) + fr) * RT_KP + (32 * s + 8 * fq) * 2); }
;                       __builtin_amdgcn_sched_barrier(0);
;                       __builtin_amdgcn_s_setprio(1);
; #pragma unroll
;                       for (int s = 0; s < 8; ++s) { Dp[0] = __builtin_amdgcn_mfma_f32_16x16x32_bf16(Ka[s], Qf[s], Dp[0], 0, 0, 0); Dp[1] = __builtin_amdgcn_mfma_f32_16x16x32_bf16(Kb[s], Qf[s], Dp[1], 0, 0, 0); }
;                       __builtin_amdgcn_s_setprio(0);
;                       __builtin_amdgcn_sched_barrier(0);
;                   }
.LBB0_439:
	s_waitcnt lgkmcnt(0)
	s_barrier
	s_waitcnt vmcnt(8)
	ds_write_b128 v186, v[2:5]
	ds_write_b128 v187, v[6:9]
	ds_write_b128 v188, v[10:13]
	ds_write_b128 v189, v[14:17]
	ds_write_b128 v190, v[18:21]
	ds_write_b128 v191, v[22:25]
	ds_write_b128 v192, v[26:29]
	ds_write_b128 v193, v[34:37]
	v_lshlrev_b32_e32 v2, 16, v46
	v_and_b32_e32 v3, 0xffff0000, v46
	v_lshlrev_b32_e32 v4, 16, v47
	v_and_b32_e32 v5, 0xffff0000, v47
	v_lshlrev_b32_e32 v6, 16, v48
	v_and_b32_e32 v7, 0xffff0000, v48
	v_lshlrev_b32_e32 v8, 16, v49
	v_and_b32_e32 v9, 0xffff0000, v49
	v_mul_f32_e32 v2, v205, v2
	v_mul_f32_e32 v3, v205, v3
	v_mul_f32_e32 v4, v205, v4
	v_mul_f32_e32 v5, v205, v5
	v_mul_f32_e32 v6, v205, v6
	v_mul_f32_e32 v7, v205, v7
	v_mul_f32_e32 v8, v205, v8
	v_mul_f32_e32 v9, v205, v9
	v_cvt_pk_bf16_f32 v2, v2, v3
	v_cvt_pk_bf16_f32 v3, v4, v5
	v_cvt_pk_bf16_f32 v4, v6, v7
	v_cvt_pk_bf16_f32 v5, v8, v9
	ds_write_b128 v195, v[2:5]
	v_lshlrev_b32_e32 v2, 16, v50
	v_and_b32_e32 v3, 0xffff0000, v50
	v_lshlrev_b32_e32 v4, 16, v51
	v_and_b32_e32 v5, 0xffff0000, v51
	v_lshlrev_b32_e32 v6, 16, v52
	v_and_b32_e32 v7, 0xffff0000, v52
	v_lshlrev_b32_e32 v8, 16, v53
	v_and_b32_e32 v9, 0xffff0000, v53
	v_mul_f32_e32 v2, v115, v2
	v_mul_f32_e32 v3, v115, v3
	v_mul_f32_e32 v4, v115, v4
	v_mul_f32_e32 v5, v115, v5
	v_mul_f32_e32 v6, v115, v6
	v_mul_f32_e32 v7, v115, v7
	v_mul_f32_e32 v8, v115, v8
	v_mul_f32_e32 v9, v115, v9
	v_cvt_pk_bf16_f32 v2, v2, v3
	v_cvt_pk_bf16_f32 v3, v4, v5
	v_cvt_pk_bf16_f32 v4, v6, v7
	v_cvt_pk_bf16_f32 v5, v8, v9
	ds_write_b128 v196, v[2:5]
	v_mov_b32_e32 v6, 0
	s_and_b64 vcc, exec, s[76:77]
	v_mov_b32_e32 v2, 0
	v_mov_b32_e32 v3, 0
	v_mov_b32_e32 v4, 0
	v_mov_b32_e32 v5, 0
	v_mov_b32_e32 v8, 0
	v_mov_b32_e32 v9, 0
	v_mov_b32_e32 v10, 0
	v_mov_b32_e32 v11, 0
	s_waitcnt lgkmcnt(0)
	s_barrier
	s_waitcnt vmcnt(0)
	s_cbranch_vccnz .LBB0_441
	ds_read_b128 v[2:5], v169
	ds_read_b128 v[8:11], v169 offset:64
	ds_read_b128 v[12:15], v169 offset:8448
	ds_read_b128 v[16:19], v169 offset:8512
	ds_read_b128 v[20:23], v169 offset:128
	ds_read_b128 v[24:27], v169 offset:192
	ds_read_b128 v[34:37], v169 offset:8576
	ds_read_b128 v[46:49], v169 offset:8640
	ds_read_b128 v[50:53], v169 offset:256
	ds_read_b128 v[78:81], v169 offset:320
	ds_read_b128 v[82:85], v169 offset:8704
	ds_read_b128 v[86:89], v169 offset:8768
	ds_read_b128 v[90:93], v169 offset:384
	ds_read_b128 v[94:97], v169 offset:448
	ds_read_b128 v[206:209], v169 offset:8832
	ds_read_b128 v[210:213], v169 offset:8896
	s_setprio 1
	s_waitcnt lgkmcnt(14)
	v_mfma_f32_16x16x32_bf16 v[2:5], v[2:5], v[30:33], 0
	s_waitcnt lgkmcnt(13)
	v_mfma_f32_16x16x32_bf16 v[12:15], v[12:15], v[30:33], 0
	v_mfma_f32_16x16x32_bf16 v[2:5], v[8:11], v[38:41], v[2:5]
	s_waitcnt lgkmcnt(12)
	v_mfma_f32_16x16x32_bf16 v[8:11], v[16:19], v[38:41], v[12:15]
	s_waitcnt lgkmcnt(11)
	v_mfma_f32_16x16x32_bf16 v[2:5], v[20:23], v[42:45], v[2:5]
	s_waitcnt lgkmcnt(9)
	v_mfma_f32_16x16x32_bf16 v[8:11], v[34:37], v[42:45], v[8:11]
	v_mfma_f32_16x16x32_bf16 v[2:5], v[24:27], v[54:57], v[2:5]
	s_waitcnt lgkmcnt(8)
	v_mfma_f32_16x16x32_bf16 v[8:11], v[46:49], v[54:57], v[8:11]
	s_waitcnt lgkmcnt(7)
	v_mfma_f32_16x16x32_bf16 v[2:5], v[50:53], v[58:61], v[2:5]
	s_waitcnt lgkmcnt(5)
	v_mfma_f32_16x16x32_bf16 v[8:11], v[82:85], v[58:61], v[8:11]
	v_mfma_f32_16x16x32_bf16 v[2:5], v[78:81], v[62:65], v[2:5]
	s_waitcnt lgkmcnt(4)
	v_mfma_f32_16x16x32_bf16 v[8:11], v[86:89], v[62:65], v[8:11]
	s_waitcnt lgkmcnt(3)
	v_mfma_f32_16x16x32_bf16 v[2:5], v[90:93], v[66:69], v[2:5]
	s_waitcnt lgkmcnt(1)
	v_mfma_f32_16x16x32_bf16 v[12:15], v[206:209], v[66:69], v[8:11]
	v_mfma_f32_16x16x32_bf16 v[8:11], v[94:97], v[70:73], v[2:5]
	s_waitcnt lgkmcnt(0)
	v_mfma_f32_16x16x32_bf16 v[2:5], v[210:213], v[70:73], v[12:15]
	s_setprio 0

; #define LAS __attribute__((address_space(3)))
; __global__ void __launch_bounds__(NTHR, 2) mega(Params p, int lo, int hi) {
;     extern __shared__ __attribute__((aligned(16))) unsigned char lds_raw[];
;     LAS unsigned char* lds = (LAS unsigned char*)lds_raw;
	.amdhsa_kernel _ZN12_GLOBAL__N_14megaENS_6ParamsEii
		.amdhsa_group_segment_fixed_size 0
		.amdhsa_private_segment_fixed_size 0
		.amdhsa_kernarg_size 568
		.amdhsa_user_sgpr_count 2
		.amdhsa_user_sgpr_dispatch_ptr 0
		.amdhsa_user_sgpr_queue_ptr 0
		.amdhsa_user_sgpr_kernarg_segment_ptr 1
		.amdhsa_user_sgpr_dispatch_id 0
		.amdhsa_user_sgpr_kernarg_preload_length 0
		.amdhsa_user_sgpr_kernarg_preload_offset 0
		.amdhsa_user_sgpr_private_segment_size 0
		.amdhsa_uses_dynamic_stack 0
		.amdhsa_enable_private_segment 0
		.amdhsa_system_sgpr_workgroup_id_x 1
		.amdhsa_system_sgpr_workgroup_id_y 0
		.amdhsa_system_sgpr_workgroup_id_z 0
		.amdhsa_system_sgpr_workgroup_info 0
		.amdhsa_system_vgpr_workitem_id 0
		.amdhsa_next_free_vgpr 256
		.amdhsa_next_free_sgpr 102
		.amdhsa_accum_offset 256
		.amdhsa_reserve_vcc 1
		.amdhsa_float_round_mode_32 0
		.amdhsa_float_round_mode_16_64 0
		.amdhsa_float_denorm_mode_32 3
		.amdhsa_float_denorm_mode_16_64 3
		.amdhsa_dx10_clamp 1
		.amdhsa_ieee_mode 1
		.amdhsa_fp16_overflow 0
		.amdhsa_tg_split 0
		.amdhsa_exception_fp_ieee_invalid_op 0
		.amdhsa_exception_fp_denorm_src 0
		.amdhsa_exception_fp_ieee_div_zero 0
		.amdhsa_exception_fp_ieee_overflow 0
		.amdhsa_exception_fp_ieee_underflow 0
		.amdhsa_exception_fp_ieee_inexact 0
		.amdhsa_exception_int_div_zero 0
	.end_amdhsa_kernel

; #define LAS __attribute__((address_space(3)))
; __global__ void __launch_bounds__(NTHR, 2) mega(Params p, int lo, int hi) {
;     extern __shared__ __attribute__((aligned(16))) unsigned char lds_raw[];
;     LAS unsigned char* lds = (LAS unsigned char*)lds_raw;
amdhsa.kernels:
  - .agpr_count:     0
    .args:
      - .offset:         0
        .size:           304
        .value_kind:     by_value
      - .offset:         304
        .size:           4
        .value_kind:     by_value
      - .offset:         308
        .size:           4
        .value_kind:     by_value
      - .offset:         312
        .size:           4
        .value_kind:     hidden_block_count_x
      - .offset:         316
        .size:           4
        .value_kind:     hidden_block_count_y
      - .offset:         320
        .size:           4
        .value_kind:     hidden_block_count_z
      - .offset:         324
        .size:           2
        .value_kind:     hidden_group_size_x
      - .offset:         326
        .size:           2
        .value_kind:     hidden_group_size_y
      - .offset:         328
        .size:           2
        .value_kind:     hidden_group_size_z
      - .offset:         330
        .size:           2
        .value_kind:     hidden_remainder_x
      - .offset:         332
        .size:           2
        .value_kind:     hidden_remainder_y
      - .offset:         334
        .size:           2
        .value_kind:     hidden_remainder_z
      - .offset:         352
        .size:           8
        .value_kind:     hidden_global_offset_x
      - .offset:         360
        .size:           8
        .value_kind:     hidden_global_offset_y
      - .offset:         368
        .size:           8
        .value_kind:     hidden_global_offset_z
      - .offset:         376
        .size:           2
        .value_kind:     hidden_grid_dims
      - .offset:         432
        .size:           4
        .value_kind:     hidden_dynamic_lds_size
    .group_segment_fixed_size: 0
    .kernarg_segment_align: 8
    .kernarg_segment_size: 568
    .language:       OpenCL C
    .language_version:
      - 2
      - 0
    .max_flat_workgroup_size: 512
    .name:           _ZN12_GLOBAL__N_14megaENS_6ParamsEii
    .private_segment_fixed_size: 0
    .sgpr_count:     108
    .sgpr_spill_count: 293
    .symbol:         _ZN12_GLOBAL__N_14megaENS_6ParamsEii.kd
    .uniform_work_group_size: 1
    .uses_dynamic_stack: false
    .vgpr_count:     256
    .vgpr_spill_count: 0
    .wavefront_size: 64
